# GEMM3 epilogue head: all global loads (conv weights, ssq row, ssq rows 14/15) issued before the unit K-loop into v246-v249; no global round trip before the first epilogue barrier
# speedup vs baseline: 1.0152x; 1.0009x over previous
; #define PG8_LAS __attribute__((address_space(3)))
; template <class Epi, class Sched, bool ALIGN_EPI = false, bool SP2 = false, bool A_TILED = false, bool B_TILED = false>
; __device__ __forceinline__ void gemm_phase(PG8_LAS unsigned char* lds, const Gemm g, const Sched& S, const Epi& E) {
;     ...
;         for (int a = 0; a < 2; ++a)
; #pragma unroll
;             for (int b = 0; b < 2; ++b)
; #pragma unroll
;                 for (int m = 0; m < 4; ++m)
; #pragma unroll
;                     for (int n = 0; n < 2; ++n) acc[a][b][m][n] = (f32x4){0.f, 0.f, 0.f, 0.f};
;     __device__ __forceinline__ void operator()(const f32x4 (&acc)[2][2][4][2], const Unit& u, int wr, int wc, int fr, int fq) const {
;     ...
;         const float* sq = ssq + u.pm * BM + wr * 64 + fr;
;     ...
;         PG8_LAS float* const T = E - 2048;
;         { const int tid_ = threadIdx.x; if (tid_ < 256) E[1024 + tid_] = 1.0f / sqrtf(ssq[u.pm * BM + tid_] * (1.0f / DM) + EPS);
;           else { const int wv_ = __builtin_amdgcn_readfirstlane(tid_ >> 6) - 4; int l2_ = 2 * (tid_ & 63); asm volatile("" : "+v"(l2_));
;                  const float* src_ = ((wv_ == 3) ? cb : cw + (size_t)wv_ * DFF) + u.pn * 128; typedef float f32x2e __attribute__((ext_vector_type(2)));
;                  *(PG8_LAS f32x2e*)(T + wv_ * 128 + l2_) = *(const f32x2e*)(src_ + l2_); } }
.LBB0_725:
	s_mov_b32 s64, s16
	s_ashr_i32 s65, s16, 31
	s_lshl_b64 s[12:13], s[64:65], 21
	s_add_u32 s70, s88, s12
	s_addc_u32 s71, s89, s13
	s_and_b64 s[12:13], s[68:69], exec
	s_mov_b32 s66, s17
	s_cselect_b32 s7, s71, s9
	s_cselect_b32 s14, s70, s8
	s_ashr_i32 s67, s17, 31
	s_lshl_b64 s[12:13], s[66:67], 21
	s_add_u32 s72, s90, s12
	s_addc_u32 s73, s91, s13
	s_and_b64 s[12:13], s[68:69], exec
	s_cselect_b32 s15, s73, s11
	s_cselect_b32 s16, s72, s10
	s_add_u32 s8, s8, 0x100080
	s_addc_u32 s9, s9, 0
	s_add_u32 s17, s10, 0x100
	v_mov_b32_e32 v6, 0
	s_addc_u32 s18, s11, 0
	s_mov_b32 s19, -2
	v_mov_b32_e32 v7, v6
	v_mov_b32_e32 v8, v6
	v_mov_b32_e32 v9, v6
	v_mov_b32_e32 v70, v6
	v_mov_b32_e32 v71, v6
	v_mov_b32_e32 v72, v6
	v_mov_b32_e32 v73, v6
	v_mov_b32_e32 v18, v6
	v_mov_b32_e32 v19, v6
	v_mov_b32_e32 v20, v6
	v_mov_b32_e32 v21, v6
	v_mov_b32_e32 v82, v6
	v_mov_b32_e32 v83, v6
	v_mov_b32_e32 v84, v6
	v_mov_b32_e32 v85, v6
	v_mov_b32_e32 v26, v6
	v_mov_b32_e32 v27, v6
	v_mov_b32_e32 v28, v6
	v_mov_b32_e32 v29, v6
	v_mov_b32_e32 v90, v6
	v_mov_b32_e32 v91, v6
	v_mov_b32_e32 v92, v6
	v_mov_b32_e32 v93, v6
	v_mov_b32_e32 v34, v6
	v_mov_b32_e32 v35, v6
	v_mov_b32_e32 v36, v6
	v_mov_b32_e32 v37, v6
	v_mov_b32_e32 v98, v6
	v_mov_b32_e32 v99, v6
	v_mov_b32_e32 v100, v6
	v_mov_b32_e32 v101, v6
	v_mov_b32_e32 v14, v6
	v_mov_b32_e32 v15, v6
	v_mov_b32_e32 v16, v6
	v_mov_b32_e32 v17, v6
	v_mov_b32_e32 v78, v6
	v_mov_b32_e32 v79, v6
	v_mov_b32_e32 v80, v6
	v_mov_b32_e32 v81, v6
	v_mov_b32_e32 v10, v6
	v_mov_b32_e32 v11, v6
	v_mov_b32_e32 v12, v6
	v_mov_b32_e32 v13, v6
	v_mov_b32_e32 v74, v6
	v_mov_b32_e32 v75, v6
	v_mov_b32_e32 v76, v6
	v_mov_b32_e32 v77, v6
	v_mov_b32_e32 v22, v6
	v_mov_b32_e32 v23, v6
	v_mov_b32_e32 v24, v6
	v_mov_b32_e32 v25, v6
	v_mov_b32_e32 v86, v6
	v_mov_b32_e32 v87, v6
	v_mov_b32_e32 v88, v6
	v_mov_b32_e32 v89, v6
	v_mov_b32_e32 v30, v6
	v_mov_b32_e32 v31, v6
	v_mov_b32_e32 v32, v6
	v_mov_b32_e32 v33, v6
	v_mov_b32_e32 v94, v6
	v_mov_b32_e32 v95, v6
	v_mov_b32_e32 v96, v6
	v_mov_b32_e32 v97, v6
	v_mov_b32_e32 v38, v6
	v_mov_b32_e32 v39, v6
	v_mov_b32_e32 v40, v6
	v_mov_b32_e32 v41, v6
	v_mov_b32_e32 v102, v6
	v_mov_b32_e32 v103, v6
	v_mov_b32_e32 v104, v6
	v_mov_b32_e32 v105, v6
	s_waitcnt vmcnt(0)
	v_mov_b32_e32 v50, v6
	v_mov_b32_e32 v51, v6
	v_mov_b32_e32 v52, v6
	v_mov_b32_e32 v53, v6
	v_mov_b32_e32 v114, v6
	v_mov_b32_e32 v115, v6
	v_mov_b32_e32 v116, v6
	v_mov_b32_e32 v117, v6
	v_mov_b32_e32 v58, v6
	v_mov_b32_e32 v59, v6
	v_mov_b32_e32 v60, v6
	v_mov_b32_e32 v61, v6
	v_mov_b32_e32 v142, v6
	v_mov_b32_e32 v143, v6
	v_mov_b32_e32 v144, v6
	v_mov_b32_e32 v145, v6
	v_mov_b32_e32 v66, v6
	v_mov_b32_e32 v67, v6
	v_mov_b32_e32 v68, v6
	v_mov_b32_e32 v69, v6
	v_mov_b32_e32 v118, v6
	v_mov_b32_e32 v119, v6
	v_mov_b32_e32 v120, v6
	v_mov_b32_e32 v121, v6
	v_mov_b32_e32 v46, v6
	v_mov_b32_e32 v47, v6
	v_mov_b32_e32 v48, v6
	v_mov_b32_e32 v49, v6
	v_mov_b32_e32 v110, v6
	v_mov_b32_e32 v111, v6
	v_mov_b32_e32 v112, v6
	v_mov_b32_e32 v113, v6
	v_mov_b32_e32 v42, v6
	v_mov_b32_e32 v43, v6
	v_mov_b32_e32 v44, v6
	v_mov_b32_e32 v45, v6
	v_mov_b32_e32 v106, v6
	v_mov_b32_e32 v107, v6
	v_mov_b32_e32 v108, v6
	v_mov_b32_e32 v109, v6
	v_mov_b32_e32 v54, v6
	v_mov_b32_e32 v55, v6
	v_mov_b32_e32 v56, v6
	v_mov_b32_e32 v57, v6
	v_mov_b32_e32 v122, v6
	v_mov_b32_e32 v123, v6
	v_mov_b32_e32 v124, v6
	v_mov_b32_e32 v125, v6
	v_mov_b32_e32 v62, v6
	v_mov_b32_e32 v63, v6
	v_mov_b32_e32 v64, v6
	v_mov_b32_e32 v65, v6
	v_mov_b32_e32 v146, v6
	v_mov_b32_e32 v147, v6
	v_mov_b32_e32 v148, v6
	v_mov_b32_e32 v149, v6
	s_lshl_b32 s98, s76, 8
	s_ashr_i32 s99, s98, 31
	s_lshl_b64 s[98:99], s[98:99], 2
	v_readlane_b32 s100, v255, 7
	v_readlane_b32 s101, v255, 8
	s_add_u32 s98, s100, s98
	s_addc_u32 s99, s101, s99
	v_mov_b32_e32 v250, v199
	v_ashrrev_i32_e32 v251, 31, v199
	v_lshl_add_u64 v[250:251], v[250:251], 2, s[98:99]
	global_load_dword v248, v[250:251], off offset:192
	global_load_dword v249, v[250:251], off offset:704
	s_cmp_eq_u64 s[4:5], 0
	s_cbranch_scc0 .Lg3h_w47
	s_lshl_b32 s98, s76, 8
	v_or_b32_e32 v252, s98, v0
	v_ashrrev_i32_e32 v253, 31, v252
	v_lshl_add_u64 v[252:253], v[252:253], 2, s[44:45]
	global_load_dword v246, v[252:253], off
	s_branch .Lg3h_done
.Lg3h_w47:
	s_load_dwordx2 s[98:99], s[0:1], 0xb8
	s_load_dwordx2 s[100:101], s[0:1], 0xc0
	v_readfirstlane_b32 vcc_lo, v0
	s_lshr_b32 vcc_lo, vcc_lo, 6
	s_add_i32 vcc_lo, vcc_lo, -4
	s_waitcnt lgkmcnt(0)
	s_cmp_eq_u32 vcc_lo, 3
	s_cbranch_scc1 .Lg3h_w7
	s_mul_i32 vcc_lo, vcc_lo, 0xac00
	s_add_u32 s100, s98, vcc_lo
	s_addc_u32 s101, s99, 0
.Lg3h_w7:
	s_lshl_b32 vcc_lo, s6, 9
	s_add_u32 s100, s100, vcc_lo
	s_addc_u32 s101, s101, 0
	v_mov_b32_e32 v252, v204
	v_ashrrev_i32_e32 v253, 31, v204
	v_lshl_add_u64 v[252:253], v[252:253], 2, s[100:101]
	global_load_dwordx2 v[246:247], v[252:253], off
; #define PG8_STAGE(bufoff, gbase, voff) do { _Pragma("unroll") for (int _i = 0; _i < 2; ++_i) \
;         __builtin_amdgcn_global_load_lds((const unsigned*)((const char*)(gbase) + (voff)[_i]), (PG8_LAS unsigned*)(lds + (bufoff) + ldsw + _i * 8192), 16, 0, 0); } while (0)
; #define PG8_LDA(dst, b, h) do { _Pragma("unroll") for (int m = 0; m < 4; ++m) _Pragma("unroll") for (int k = 0; k < 2; ++k) dst[m][k] = *(const PG8_LAS bf16x8*)(lds + PG8_SA(b, h) + aoff + m * 2048 + k * 1024); } while (0)
; #define PG8_LDB(dst, b, h) do { _Pragma("unroll") for (int n = 0; n < 2; ++n) _Pragma("unroll") for (int k = 0; k < 2; ++k) dst[n][k] = *(const PG8_LAS bf16x8*)(lds + PG8_SB(b, h) + boff + n * 2048 + k * 1024); } while (0)
; #define PG8_MMA(ai, bj, At, Bt) do { __builtin_amdgcn_s_setprio(1); _Pragma("unroll") for (int m = 0; m < 4; ++m) _Pragma("unroll") for (int n = 0; n < 2; ++n) _Pragma("unroll") for (int k = 0; k < 2; ++k) \
;         acc[ai][bj][m][n] = __builtin_amdgcn_mfma_f32_16x16x32_bf16(Bt[n][k], At[m][k], acc[ai][bj][m][n], 0, 0, 0); __builtin_amdgcn_s_setprio(0); } while (0)
; #define PG8_WAIT_V(n) asm volatile("s_waitcnt vmcnt(" #n ")" ::: "memory")
; #define PG8_WAIT_L(n) asm volatile("s_waitcnt lgkmcnt(" #n ")" ::: "memory")
; #define PG8_BAR __builtin_amdgcn_s_barrier()
; template <class Epi, class Sched, bool ALIGN_EPI = false, bool SP2 = false, bool A_TILED = false, bool B_TILED = false>
; __device__ __forceinline__ void gemm_phase(PG8_LAS unsigned char* lds, const Gemm g, const Sched& S, const Epi& E) {
;     ...
;         for (int t = 0; t < nt; t += 2) {
;             const bool last = (t == nt - 2);
;             const char* a1 = cA + (size_t)(t + 1) * kstepA;
;             const char* a2 = last ? nA : cA + (size_t)(t + 2) * kstepA; const char* b2 = last ? nB : cB + (size_t)(t + 2) * kstepB;
;             const char* a3 = a2 + kstepA; const char* b3 = b2 + kstepB;
;             if (last && has_next) S.a_ready(nxt);
;             if constexpr (SP2) {
;             PG8_LDB(B0, 0, 0); PG8_LDB(B1, 0, 1); PG8_SCHED; PG8_LDA(At, 0, 0); PG8_STAGE(PG8_SA(1, 1), a1 + hstepA, voffA);
;             PG8_WAIT_V(8); PG8_WAIT_L(0); PG8_BAR; PG8_MMA(0, 0, At, B0); PG8_MMA(0, 1, At, B1); PG8_BAR; PG8_SCHED;
;             PG8_LDA(At, 0, 1); PG8_STAGE(PG8_SB(0, 0), b2, voffB); PG8_STAGE(PG8_SB(0, 1), b2 + hstepB, voffB); PG8_STAGE(PG8_SA(0, 0), a2, voffA);
.Lg3h_done:
.LBB0_726:
	ds_read_b128 v[126:129], v207
	ds_read_b128 v[130:133], v207 offset:1024
	ds_read_b128 v[134:137], v207 offset:2048
	ds_read_b128 v[138:141], v207 offset:3072
	ds_read_b128 v[150:153], v208
	ds_read_b128 v[154:157], v208 offset:1024
	ds_read_b128 v[158:161], v208 offset:2048
	ds_read_b128 v[162:165], v208 offset:3072
	s_add_u32 s10, s8, 0xfff00080
	s_addc_u32 s11, s9, -1
	s_cmp_eq_u32 s19, 60
	s_cselect_b32 s13, s7, s11
	s_cselect_b32 s12, s14, s10
	s_cselect_b32 s11, s15, s18
	s_cselect_b32 s10, s16, s17
	v_lshl_add_u64 v[236:237], s[8:9], 0, v[180:181]
	s_add_i32 m0, s93, 0xc000
	ds_read_b128 v[166:169], v209
	ds_read_b128 v[184:187], v209 offset:1024
	ds_read_b128 v[190:193], v209 offset:2048
	ds_read_b128 v[216:219], v209 offset:3072
	ds_read_b128 v[220:223], v209 offset:4096
	ds_read_b128 v[224:227], v209 offset:5120
	ds_read_b128 v[228:231], v209 offset:6144
	ds_read_b128 v[232:235], v209 offset:7168
	global_load_lds_dwordx4 v[236:237], off
	v_lshl_add_u64 v[236:237], s[8:9], 0, v[182:183]
	s_add_i32 m0, s93, 0xe000
	s_nop 0
	global_load_lds_dwordx4 v[236:237], off
	s_waitcnt vmcnt(8)
	s_waitcnt lgkmcnt(0)
	s_barrier
	v_mfma_f32_16x16x32_bf16 v[146:149], v[126:129], v[166:169], v[146:149]
	v_mfma_f32_16x16x32_bf16 v[62:65], v[134:137], v[166:169], v[62:65]
	v_mfma_f32_16x16x32_bf16 v[122:125], v[126:129], v[190:193], v[122:125]
	v_mfma_f32_16x16x32_bf16 v[54:57], v[134:137], v[190:193], v[54:57]
	v_mfma_f32_16x16x32_bf16 v[106:109], v[126:129], v[220:223], v[106:109]
	v_mfma_f32_16x16x32_bf16 v[42:45], v[134:137], v[220:223], v[42:45]
	v_mfma_f32_16x16x32_bf16 v[110:113], v[126:129], v[228:231], v[110:113]
	v_mfma_f32_16x16x32_bf16 v[46:49], v[134:137], v[228:231], v[46:49]
	v_mfma_f32_16x16x32_bf16 v[146:149], v[130:133], v[184:187], v[146:149]
	v_mfma_f32_16x16x32_bf16 v[62:65], v[138:141], v[184:187], v[62:65]
	v_mfma_f32_16x16x32_bf16 v[122:125], v[130:133], v[216:219], v[122:125]
	v_mfma_f32_16x16x32_bf16 v[54:57], v[138:141], v[216:219], v[54:57]
	v_mfma_f32_16x16x32_bf16 v[106:109], v[130:133], v[224:227], v[106:109]
	v_mfma_f32_16x16x32_bf16 v[42:45], v[138:141], v[224:227], v[42:45]
	v_mfma_f32_16x16x32_bf16 v[110:113], v[130:133], v[232:235], v[110:113]
	v_mfma_f32_16x16x32_bf16 v[46:49], v[138:141], v[232:235], v[46:49]
	v_mfma_f32_16x16x32_bf16 v[118:121], v[150:153], v[166:169], v[118:121]
	v_mfma_f32_16x16x32_bf16 v[66:69], v[158:161], v[166:169], v[66:69]
	v_mfma_f32_16x16x32_bf16 v[142:145], v[150:153], v[190:193], v[142:145]
	v_mfma_f32_16x16x32_bf16 v[58:61], v[158:161], v[190:193], v[58:61]
	v_mfma_f32_16x16x32_bf16 v[114:117], v[150:153], v[220:223], v[114:117]
	v_mfma_f32_16x16x32_bf16 v[50:53], v[158:161], v[220:223], v[50:53]
	v_mfma_f32_16x16x32_bf16 v[102:105], v[150:153], v[228:231], v[102:105]
	v_mfma_f32_16x16x32_bf16 v[38:41], v[158:161], v[228:231], v[38:41]
	v_mfma_f32_16x16x32_bf16 v[118:121], v[154:157], v[184:187], v[118:121]
	v_mfma_f32_16x16x32_bf16 v[66:69], v[162:165], v[184:187], v[66:69]
	v_mfma_f32_16x16x32_bf16 v[142:145], v[154:157], v[216:219], v[142:145]
	v_mfma_f32_16x16x32_bf16 v[58:61], v[162:165], v[216:219], v[58:61]
	v_mfma_f32_16x16x32_bf16 v[114:117], v[154:157], v[224:227], v[114:117]
	v_mfma_f32_16x16x32_bf16 v[50:53], v[162:165], v[224:227], v[50:53]
	v_mfma_f32_16x16x32_bf16 v[102:105], v[154:157], v[232:235], v[102:105]
	v_mfma_f32_16x16x32_bf16 v[38:41], v[162:165], v[232:235], v[38:41]
	s_barrier
	s_add_i32 s20, s24, s92
	v_lshl_add_u64 v[236:237], s[10:11], 0, v[172:173]
	s_mov_b32 m0, s20
	ds_read_b128 v[166:169], v209 offset:16384
	ds_read_b128 v[184:187], v209 offset:17408
	ds_read_b128 v[190:193], v209 offset:18432
	ds_read_b128 v[216:219], v209 offset:19456
	ds_read_b128 v[220:223], v209 offset:20480
	ds_read_b128 v[224:227], v209 offset:21504
	ds_read_b128 v[228:231], v209 offset:22528
	ds_read_b128 v[232:235], v209 offset:23552
	global_load_lds_dwordx4 v[236:237], off
	s_add_i32 m0, s20, 0x2000
	s_add_u32 s20, s10, 0x100000
	v_lshl_add_u64 v[238:239], s[10:11], 0, v[176:177]
	s_addc_u32 s21, s11, 0
	s_add_i32 s22, s25, s92
	global_load_lds_dwordx4 v[238:239], off
	v_lshl_add_u64 v[240:241], s[20:21], 0, v[172:173]
	s_mov_b32 m0, s22
	v_lshl_add_u64 v[242:243], s[12:13], 0, v[174:175]
	global_load_lds_dwordx4 v[240:241], off
	v_lshl_add_u64 v[240:241], s[20:21], 0, v[176:177]
	s_add_i32 m0, s22, 0x2000
	s_nop 0
	global_load_lds_dwordx4 v[240:241], off
	v_lshl_add_u64 v[240:241], s[12:13], 0, v[170:171]
	s_mov_b32 m0, s93
	s_nop 0
	global_load_lds_dwordx4 v[240:241], off
	s_mov_b32 m0, s94
	s_nop 0
	global_load_lds_dwordx4 v[242:243], off
	s_waitcnt vmcnt(8)
	s_waitcnt lgkmcnt(0)
	s_barrier
; #define PG8_STAGE(bufoff, gbase, voff) do { _Pragma("unroll") for (int _i = 0; _i < 2; ++_i) \
;         __builtin_amdgcn_global_load_lds((const unsigned*)((const char*)(gbase) + (voff)[_i]), (PG8_LAS unsigned*)(lds + (bufoff) + ldsw + _i * 8192), 16, 0, 0); } while (0)
; #define PG8_LDA(dst, b, h) do { _Pragma("unroll") for (int m = 0; m < 4; ++m) _Pragma("unroll") for (int k = 0; k < 2; ++k) dst[m][k] = *(const PG8_LAS bf16x8*)(lds + PG8_SA(b, h) + aoff + m * 2048 + k * 1024); } while (0)
; #define PG8_LDB(dst, b, h) do { _Pragma("unroll") for (int n = 0; n < 2; ++n) _Pragma("unroll") for (int k = 0; k < 2; ++k) dst[n][k] = *(const PG8_LAS bf16x8*)(lds + PG8_SB(b, h) + boff + n * 2048 + k * 1024); } while (0)
; #define PG8_MMA(ai, bj, At, Bt) do { __builtin_amdgcn_s_setprio(1); _Pragma("unroll") for (int m = 0; m < 4; ++m) _Pragma("unroll") for (int n = 0; n < 2; ++n) _Pragma("unroll") for (int k = 0; k < 2; ++k) \
;         acc[ai][bj][m][n] = __builtin_amdgcn_mfma_f32_16x16x32_bf16(Bt[n][k], At[m][k], acc[ai][bj][m][n], 0, 0, 0); __builtin_amdgcn_s_setprio(0); } while (0)
; #define PG8_WAIT_V(n) asm volatile("s_waitcnt vmcnt(" #n ")" ::: "memory")
; #define PG8_WAIT_L(n) asm volatile("s_waitcnt lgkmcnt(" #n ")" ::: "memory")
; #define PG8_BAR __builtin_amdgcn_s_barrier()
; #define PG8_SCHED __builtin_amdgcn_sched_barrier(0)
; template <class Epi, class Sched, bool ALIGN_EPI = false, bool SP2 = false, bool A_TILED = false, bool B_TILED = false>
; __device__ __forceinline__ void gemm_phase(PG8_LAS unsigned char* lds, const Gemm g, const Sched& S, const Epi& E) {
;     ...
;             PG8_WAIT_V(8); PG8_WAIT_L(0); PG8_BAR; PG8_MMA(1, 0, At, B0); PG8_MMA(1, 1, At, B1); PG8_BAR; PG8_SCHED;
;             PG8_LDB(B0, 1, 0); PG8_LDB(B1, 1, 1); PG8_SCHED; PG8_LDA(At, 1, 0); PG8_STAGE(PG8_SA(0, 1), a2 + hstepA, voffA);
;             PG8_WAIT_V(8); PG8_WAIT_L(0); PG8_BAR; PG8_MMA(0, 0, At, B0); PG8_MMA(0, 1, At, B1); PG8_BAR; PG8_SCHED;
	v_mfma_f32_16x16x32_bf16 v[94:97], v[126:129], v[166:169], v[94:97]
	v_mfma_f32_16x16x32_bf16 v[30:33], v[134:137], v[166:169], v[30:33]
	v_mfma_f32_16x16x32_bf16 v[86:89], v[126:129], v[190:193], v[86:89]
	v_mfma_f32_16x16x32_bf16 v[22:25], v[134:137], v[190:193], v[22:25]
	v_mfma_f32_16x16x32_bf16 v[74:77], v[126:129], v[220:223], v[74:77]
	v_mfma_f32_16x16x32_bf16 v[10:13], v[134:137], v[220:223], v[10:13]
	v_mfma_f32_16x16x32_bf16 v[78:81], v[126:129], v[228:231], v[78:81]
	v_mfma_f32_16x16x32_bf16 v[14:17], v[134:137], v[228:231], v[14:17]
	v_mfma_f32_16x16x32_bf16 v[94:97], v[130:133], v[184:187], v[94:97]
	v_mfma_f32_16x16x32_bf16 v[30:33], v[138:141], v[184:187], v[30:33]
	v_mfma_f32_16x16x32_bf16 v[86:89], v[130:133], v[216:219], v[86:89]
	v_mfma_f32_16x16x32_bf16 v[22:25], v[138:141], v[216:219], v[22:25]
	v_mfma_f32_16x16x32_bf16 v[74:77], v[130:133], v[224:227], v[74:77]
	v_mfma_f32_16x16x32_bf16 v[10:13], v[138:141], v[224:227], v[10:13]
	v_mfma_f32_16x16x32_bf16 v[78:81], v[130:133], v[232:235], v[78:81]
	v_mfma_f32_16x16x32_bf16 v[14:17], v[138:141], v[232:235], v[14:17]
	v_mfma_f32_16x16x32_bf16 v[98:101], v[150:153], v[166:169], v[98:101]
	v_mfma_f32_16x16x32_bf16 v[34:37], v[158:161], v[166:169], v[34:37]
	v_mfma_f32_16x16x32_bf16 v[90:93], v[150:153], v[190:193], v[90:93]
	v_mfma_f32_16x16x32_bf16 v[26:29], v[158:161], v[190:193], v[26:29]
	v_mfma_f32_16x16x32_bf16 v[82:85], v[150:153], v[220:223], v[82:85]
	v_mfma_f32_16x16x32_bf16 v[18:21], v[158:161], v[220:223], v[18:21]
	v_mfma_f32_16x16x32_bf16 v[70:73], v[150:153], v[228:231], v[70:73]
	v_mfma_f32_16x16x32_bf16 v[6:9], v[158:161], v[228:231], v[6:9]
	v_mfma_f32_16x16x32_bf16 v[98:101], v[154:157], v[184:187], v[98:101]
	v_mfma_f32_16x16x32_bf16 v[34:37], v[162:165], v[184:187], v[34:37]
	v_mfma_f32_16x16x32_bf16 v[90:93], v[154:157], v[216:219], v[90:93]
	v_mfma_f32_16x16x32_bf16 v[26:29], v[162:165], v[216:219], v[26:29]
	v_mfma_f32_16x16x32_bf16 v[82:85], v[154:157], v[224:227], v[82:85]
	v_mfma_f32_16x16x32_bf16 v[18:21], v[162:165], v[224:227], v[18:21]
	v_mfma_f32_16x16x32_bf16 v[70:73], v[154:157], v[232:235], v[70:73]
	v_mfma_f32_16x16x32_bf16 v[6:9], v[162:165], v[232:235], v[6:9]
	s_barrier
	s_add_i32 s20, 0, 0x18000
	s_add_i32 s21, 0, 0x1c000
	v_add_u32_e32 v138, s20, v203
	v_add_u32_e32 v162, s21, v203
	ds_read_b128 v[126:129], v138
	ds_read_b128 v[130:133], v138 offset:1024
	ds_read_b128 v[134:137], v138 offset:2048
	ds_read_b128 v[138:141], v138 offset:3072
	ds_read_b128 v[150:153], v162
	ds_read_b128 v[154:157], v162 offset:1024
	ds_read_b128 v[158:161], v162 offset:2048
	ds_read_b128 v[162:165], v162 offset:3072
	s_add_u32 s12, s12, 0x100000
	s_addc_u32 s13, s13, 0
	s_mov_b32 m0, s95
	v_lshl_add_u64 v[244:245], s[12:13], 0, v[170:171]
	ds_read_b128 v[166:169], v209 offset:32768
	ds_read_b128 v[184:187], v209 offset:33792
	ds_read_b128 v[190:193], v209 offset:34816
	ds_read_b128 v[216:219], v209 offset:35840
	ds_read_b128 v[220:223], v209 offset:36864
	ds_read_b128 v[224:227], v209 offset:37888
	ds_read_b128 v[228:231], v209 offset:38912
	ds_read_b128 v[232:235], v209 offset:39936
	global_load_lds_dwordx4 v[244:245], off
	v_lshl_add_u64 v[244:245], s[12:13], 0, v[174:175]
	s_mov_b32 m0, s96
	s_nop 0
	global_load_lds_dwordx4 v[244:245], off
	s_waitcnt vmcnt(8)
	s_waitcnt lgkmcnt(0)
	s_barrier
	v_mfma_f32_16x16x32_bf16 v[146:149], v[126:129], v[166:169], v[146:149]
	v_mfma_f32_16x16x32_bf16 v[62:65], v[134:137], v[166:169], v[62:65]
	v_mfma_f32_16x16x32_bf16 v[122:125], v[126:129], v[190:193], v[122:125]
	v_mfma_f32_16x16x32_bf16 v[54:57], v[134:137], v[190:193], v[54:57]
	v_mfma_f32_16x16x32_bf16 v[106:109], v[126:129], v[220:223], v[106:109]
	v_mfma_f32_16x16x32_bf16 v[42:45], v[134:137], v[220:223], v[42:45]
	v_mfma_f32_16x16x32_bf16 v[110:113], v[126:129], v[228:231], v[110:113]
	v_mfma_f32_16x16x32_bf16 v[46:49], v[134:137], v[228:231], v[46:49]
	v_mfma_f32_16x16x32_bf16 v[146:149], v[130:133], v[184:187], v[146:149]
	v_mfma_f32_16x16x32_bf16 v[62:65], v[138:141], v[184:187], v[62:65]
	v_mfma_f32_16x16x32_bf16 v[122:125], v[130:133], v[216:219], v[122:125]
	v_mfma_f32_16x16x32_bf16 v[54:57], v[138:141], v[216:219], v[54:57]
	v_mfma_f32_16x16x32_bf16 v[106:109], v[130:133], v[224:227], v[106:109]
	v_mfma_f32_16x16x32_bf16 v[42:45], v[138:141], v[224:227], v[42:45]
	v_mfma_f32_16x16x32_bf16 v[110:113], v[130:133], v[232:235], v[110:113]
	v_mfma_f32_16x16x32_bf16 v[46:49], v[138:141], v[232:235], v[46:49]
	v_mfma_f32_16x16x32_bf16 v[118:121], v[150:153], v[166:169], v[118:121]
	v_mfma_f32_16x16x32_bf16 v[66:69], v[158:161], v[166:169], v[66:69]
	v_mfma_f32_16x16x32_bf16 v[142:145], v[150:153], v[190:193], v[142:145]
	v_mfma_f32_16x16x32_bf16 v[58:61], v[158:161], v[190:193], v[58:61]
	v_mfma_f32_16x16x32_bf16 v[114:117], v[150:153], v[220:223], v[114:117]
	v_mfma_f32_16x16x32_bf16 v[50:53], v[158:161], v[220:223], v[50:53]
	v_mfma_f32_16x16x32_bf16 v[102:105], v[150:153], v[228:231], v[102:105]
	v_mfma_f32_16x16x32_bf16 v[38:41], v[158:161], v[228:231], v[38:41]
	v_mfma_f32_16x16x32_bf16 v[118:121], v[154:157], v[184:187], v[118:121]
	v_mfma_f32_16x16x32_bf16 v[66:69], v[162:165], v[184:187], v[66:69]
	v_mfma_f32_16x16x32_bf16 v[142:145], v[154:157], v[216:219], v[142:145]
	v_mfma_f32_16x16x32_bf16 v[58:61], v[162:165], v[216:219], v[58:61]
	v_mfma_f32_16x16x32_bf16 v[114:117], v[154:157], v[224:227], v[114:117]
	v_mfma_f32_16x16x32_bf16 v[50:53], v[162:165], v[224:227], v[50:53]
	v_mfma_f32_16x16x32_bf16 v[102:105], v[154:157], v[232:235], v[102:105]
	v_mfma_f32_16x16x32_bf16 v[38:41], v[162:165], v[232:235], v[38:41]
	s_barrier
; #define PG8_LAS __attribute__((address_space(3)))
; #define PG8_STAGE(bufoff, gbase, voff) do { _Pragma("unroll") for (int _i = 0; _i < 2; ++_i) \
;         __builtin_amdgcn_global_load_lds((const unsigned*)((const char*)(gbase) + (voff)[_i]), (PG8_LAS unsigned*)(lds + (bufoff) + ldsw + _i * 8192), 16, 0, 0); } while (0)
; #define PG8_LDA(dst, b, h) do { _Pragma("unroll") for (int m = 0; m < 4; ++m) _Pragma("unroll") for (int k = 0; k < 2; ++k) dst[m][k] = *(const PG8_LAS bf16x8*)(lds + PG8_SA(b, h) + aoff + m * 2048 + k * 1024); } while (0)
; #define PG8_MMA(ai, bj, At, Bt) do { __builtin_amdgcn_s_setprio(1); _Pragma("unroll") for (int m = 0; m < 4; ++m) _Pragma("unroll") for (int n = 0; n < 2; ++n) _Pragma("unroll") for (int k = 0; k < 2; ++k) \
;         acc[ai][bj][m][n] = __builtin_amdgcn_mfma_f32_16x16x32_bf16(Bt[n][k], At[m][k], acc[ai][bj][m][n], 0, 0, 0); __builtin_amdgcn_s_setprio(0); } while (0)
; #define PG8_WAIT_V(n) asm volatile("s_waitcnt vmcnt(" #n ")" ::: "memory")
; #define PG8_WAIT_L(n) asm volatile("s_waitcnt lgkmcnt(" #n ")" ::: "memory")
; #define PG8_BAR __builtin_amdgcn_s_barrier()
; template <class Epi, class Sched, bool ALIGN_EPI = false, bool SP2 = false, bool A_TILED = false, bool B_TILED = false>
; __device__ __forceinline__ void gemm_phase(PG8_LAS unsigned char* lds, const Gemm g, const Sched& S, const Epi& E) {
;     ...
;             PG8_LDA(At, 1, 1); PG8_STAGE(PG8_SB(1, 0), b3, voffB); PG8_STAGE(PG8_SB(1, 1), b3 + hstepB, voffB); PG8_STAGE(PG8_SA(1, 0), a3, voffA);
;             PG8_WAIT_V(8); PG8_WAIT_L(0); PG8_BAR; PG8_MMA(1, 0, At, B0); PG8_MMA(1, 1, At, B1); PG8_BAR; PG8_SCHED;
;     __device__ __forceinline__ void operator()(const f32x4 (&acc)[2][2][4][2], const Unit& u, int wr, int wc, int fr, int fq) const {
;     ...
;         const float* sq = ssq + u.pm * BM + wr * 64 + fr;
;     ...
;         PG8_LAS float* const T = E - 2048;
;         { const int tid_ = threadIdx.x; if (tid_ < 256) E[1024 + tid_] = 1.0f / sqrtf(ssq[u.pm * BM + tid_] * (1.0f / DM) + EPS);
;           else { const int wv_ = __builtin_amdgcn_readfirstlane(tid_ >> 6) - 4; int l2_ = 2 * (tid_ & 63); asm volatile("" : "+v"(l2_));
;                  const float* src_ = ((wv_ == 3) ? cb : cw + (size_t)wv_ * DFF) + u.pn * 128; typedef float f32x2e __attribute__((ext_vector_type(2)));
;                  *(PG8_LAS f32x2e*)(T + wv_ * 128 + l2_) = *(const f32x2e*)(src_ + l2_); } }
	s_add_i32 s12, s20, s92
	v_lshl_add_u64 v[236:237], v[236:237], 0, s[46:47]
	s_mov_b32 m0, s12
	ds_read_b128 v[166:169], v209 offset:49152
	ds_read_b128 v[184:187], v209 offset:50176
	ds_read_b128 v[190:193], v209 offset:51200
	ds_read_b128 v[216:219], v209 offset:52224
	ds_read_b128 v[220:223], v209 offset:53248
	ds_read_b128 v[224:227], v209 offset:54272
	ds_read_b128 v[228:231], v209 offset:55296
	ds_read_b128 v[232:235], v209 offset:56320
	global_load_lds_dwordx4 v[236:237], off
	s_add_i32 m0, s12, 0x2000
	s_add_u32 s10, s10, 0x100080
	v_lshl_add_u64 v[236:237], v[238:239], 0, s[46:47]
	s_addc_u32 s11, s11, 0
	s_add_i32 s12, s21, s92
	global_load_lds_dwordx4 v[236:237], off
	v_lshl_add_u64 v[236:237], s[10:11], 0, v[172:173]
	s_mov_b32 m0, s12
	s_nop 0
	global_load_lds_dwordx4 v[236:237], off
	v_lshl_add_u64 v[236:237], s[10:11], 0, v[176:177]
	s_add_i32 m0, s12, 0x2000
	s_nop 0
	global_load_lds_dwordx4 v[236:237], off
	v_lshl_add_u64 v[236:237], v[240:241], 0, s[46:47]
	s_mov_b32 m0, s54
	s_nop 0
	global_load_lds_dwordx4 v[236:237], off
	v_lshl_add_u64 v[236:237], v[242:243], 0, s[46:47]
	s_mov_b32 m0, s55
	s_nop 0
	global_load_lds_dwordx4 v[236:237], off
	s_waitcnt vmcnt(8)
	s_waitcnt lgkmcnt(0)
	s_barrier
	v_mfma_f32_16x16x32_bf16 v[94:97], v[126:129], v[166:169], v[94:97]
	v_mfma_f32_16x16x32_bf16 v[30:33], v[134:137], v[166:169], v[30:33]
	v_mfma_f32_16x16x32_bf16 v[86:89], v[126:129], v[190:193], v[86:89]
	v_mfma_f32_16x16x32_bf16 v[22:25], v[134:137], v[190:193], v[22:25]
	v_mfma_f32_16x16x32_bf16 v[74:77], v[126:129], v[220:223], v[74:77]
	v_mfma_f32_16x16x32_bf16 v[10:13], v[134:137], v[220:223], v[10:13]
	v_mfma_f32_16x16x32_bf16 v[78:81], v[126:129], v[228:231], v[78:81]
	v_mfma_f32_16x16x32_bf16 v[14:17], v[134:137], v[228:231], v[14:17]
	v_mfma_f32_16x16x32_bf16 v[94:97], v[130:133], v[184:187], v[94:97]
	v_mfma_f32_16x16x32_bf16 v[30:33], v[138:141], v[184:187], v[30:33]
	v_mfma_f32_16x16x32_bf16 v[86:89], v[130:133], v[216:219], v[86:89]
	v_mfma_f32_16x16x32_bf16 v[22:25], v[138:141], v[216:219], v[22:25]
	v_mfma_f32_16x16x32_bf16 v[74:77], v[130:133], v[224:227], v[74:77]
	v_mfma_f32_16x16x32_bf16 v[10:13], v[138:141], v[224:227], v[10:13]
	v_mfma_f32_16x16x32_bf16 v[78:81], v[130:133], v[232:235], v[78:81]
	v_mfma_f32_16x16x32_bf16 v[14:17], v[138:141], v[232:235], v[14:17]
	v_mfma_f32_16x16x32_bf16 v[98:101], v[150:153], v[166:169], v[98:101]
	v_mfma_f32_16x16x32_bf16 v[34:37], v[158:161], v[166:169], v[34:37]
	v_mfma_f32_16x16x32_bf16 v[90:93], v[150:153], v[190:193], v[90:93]
	v_mfma_f32_16x16x32_bf16 v[26:29], v[158:161], v[190:193], v[26:29]
	v_mfma_f32_16x16x32_bf16 v[82:85], v[150:153], v[220:223], v[82:85]
	v_mfma_f32_16x16x32_bf16 v[18:21], v[158:161], v[220:223], v[18:21]
	v_mfma_f32_16x16x32_bf16 v[70:73], v[150:153], v[228:231], v[70:73]
	v_mfma_f32_16x16x32_bf16 v[6:9], v[158:161], v[228:231], v[6:9]
	v_mfma_f32_16x16x32_bf16 v[98:101], v[154:157], v[184:187], v[98:101]
	v_mfma_f32_16x16x32_bf16 v[34:37], v[162:165], v[184:187], v[34:37]
	v_mfma_f32_16x16x32_bf16 v[90:93], v[154:157], v[216:219], v[90:93]
	v_mfma_f32_16x16x32_bf16 v[26:29], v[162:165], v[216:219], v[26:29]
	v_mfma_f32_16x16x32_bf16 v[82:85], v[154:157], v[224:227], v[82:85]
	v_mfma_f32_16x16x32_bf16 v[18:21], v[162:165], v[224:227], v[18:21]
	v_mfma_f32_16x16x32_bf16 v[70:73], v[154:157], v[232:235], v[70:73]
	v_mfma_f32_16x16x32_bf16 v[6:9], v[162:165], v[232:235], v[6:9]
	s_barrier
	s_add_i32 s19, s19, 2
	s_add_u32 s8, s8, 0x100
	s_addc_u32 s9, s9, 0
	s_add_u32 s17, s17, 0x100
	s_addc_u32 s18, s18, 0
	s_cmp_gt_u32 s19, 61
	s_cbranch_scc0 .LBB0_726
	s_and_b64 vcc, exec, s[56:57]
	s_cbranch_vccz .LBB0_729
	s_barrier
.LBB0_729:
	v_mov_b32_e32 v128, v202
	v_mov_b32_e32 v186, v199
	s_lshl_b32 s10, s6, 7
	s_and_saveexec_b64 s[6:7], s[4:5]
	s_xor_b64 s[6:7], exec, s[6:7]
	s_cbranch_execz .LBB0_733
	v_mov_b32_e32 v126, v204
	s_nop 0
	v_readfirstlane_b32 s8, v0
	s_lshr_b32 s12, s8, 6
	s_add_i32 s12, s12, -4
	s_cmp_eq_u32 s12, 3
	s_waitcnt lgkmcnt(0)
	s_mov_b64 s[8:9], s[18:19]
	s_cbranch_scc1 .LBB0_732
	s_nop 0
	s_mul_i32 s8, s12, 0xac00
	s_mul_hi_i32 s9, s12, 0xac00
	s_waitcnt lgkmcnt(0)
	s_add_u32 s8, s16, s8
	s_addc_u32 s9, s17, s9
.LBB0_732:
	s_ashr_i32 s11, s10, 31
	s_lshl_b64 s[14:15], s[10:11], 2
	s_add_u32 s8, s8, s14
	s_addc_u32 s9, s9, s15
	v_ashrrev_i32_e32 v127, 31, v126
	v_lshl_add_u64 v[130:131], v[126:127], 2, s[8:9]
	s_nop 0
	s_lshl_b32 s8, s12, 9
	s_add_i32 s8, s8, 0
	v_lshl_add_u32 v126, v126, 2, s8
	v_add_u32_e32 v126, 0x20000, v126
	s_waitcnt vmcnt(0)
	v_mov_b32_e32 v130, v246
	v_mov_b32_e32 v131, v247
	ds_write_b64 v126, v[130:131]
.LBB0_733:
	s_or_saveexec_b64 s[8:9], s[6:7]
	s_lshl_b32 s74, s76, 8
	s_xor_b64 exec, exec, s[8:9]
	s_cbranch_execz .LBB0_735
	v_or_b32_e32 v126, s74, v0
	v_ashrrev_i32_e32 v127, 31, v126
	v_lshl_add_u64 v[126:127], v[126:127], 2, s[44:45]
	s_nop 0
	s_waitcnt vmcnt(0)
	v_mov_b32_e32 v126, v246
	v_fmamk_f32 v126, v126, 0x39800000, v210
	v_mul_f32_e32 v127, 0x4f800000, v126
	v_cmp_gt_f32_e32 vcc, s27, v126
	s_nop 1
	v_cndmask_b32_e32 v126, v126, v127, vcc
	v_sqrt_f32_e32 v127, v126
	s_nop 0
	v_add_u32_e32 v129, -1, v127
	v_add_u32_e32 v130, 1, v127
	v_fma_f32 v131, -v129, v127, v126
	v_fma_f32 v132, -v130, v127, v126
	v_cmp_ge_f32_e64 s[6:7], 0, v131
	s_nop 1
	v_cndmask_b32_e64 v127, v127, v129, s[6:7]
	v_cmp_lt_f32_e64 s[6:7], 0, v132
	s_nop 1
	v_cndmask_b32_e64 v127, v127, v130, s[6:7]
	v_mul_f32_e32 v129, 0x37800000, v127
	v_cndmask_b32_e32 v127, v127, v129, vcc
	v_cmp_class_f32_e32 vcc, v126, v211
	s_nop 1
	v_cndmask_b32_e32 v126, v127, v126, vcc
	v_div_scale_f32 v127, s[6:7], v126, v126, 1.0
	v_rcp_f32_e32 v129, v127
	v_div_scale_f32 v130, vcc, 1.0, v126, 1.0
	v_fma_f32 v131, -v127, v129, 1.0
	v_fmac_f32_e32 v129, v131, v129
	v_mul_f32_e32 v131, v130, v129
	v_fma_f32 v132, -v127, v131, v130
	v_fmac_f32_e32 v131, v132, v129
	v_fma_f32 v127, -v127, v131, v130
	v_div_fmas_f32 v127, v127, v129, v131
	v_div_fixup_f32 v126, v127, v126, 1.0
	ds_write_b32 v205, v126 offset:4096
; #define PG8_LAS __attribute__((address_space(3)))
; #define RSTD(ai_, m_) (1.0f / sqrtf(sq[(ai_) * HALF + (m_) * 16] * (1.0f / DM) + EPS))
;     __device__ __forceinline__ void operator()(const f32x4 (&acc)[2][2][4][2], const Unit& u, int wr, int wc, int fr, int fq) const {
;     ...
;         if (fr >= 14) {
; #pragma unroll
;             for (int ai = 0; ai < 2; ++ai)
; #pragma unroll
;                 for (int n = 0; n < 2; ++n) *(PG8_LAS f32x4*)(E + ((ai * 2 + wr) * 2 + (fr - 14)) * 128 + jl + 4 * n) = acc[ai][0][3][n] * RSTD(ai, 3);
;             if (!sample && wr == 1) {
; #pragma unroll
;                 for (int n = 0; n < 2; ++n) { const f32x4 gh = acc[1][0][3][n] * RSTD(1, 3); *(f32x4*)(fix + ((size_t)u.pm * 2 + (fr - 14)) * DFF + j0 + 4 * n) = gh;
;                     if ((u.pm & 7) == 7) *(f32x4*)(out + O_PFFN + ((size_t)(u.pm >> 3) * 2 + (fr - 14)) * DFF + j0 + 4 * n) = gh; }
.LBB0_735:
	s_or_b64 exec, exec, s[8:9]
	s_cmp_lt_i32 s76, 32
	s_cselect_b64 s[80:81], -1, 0
	s_cmp_gt_i32 s76, 31
	s_cselect_b64 s[22:23], -1, 0
	v_cmp_gt_i32_e32 vcc, 14, v186
	s_and_saveexec_b64 s[6:7], vcc
	s_xor_b64 s[6:7], exec, s[6:7]
	s_and_b64 s[78:79], s[38:39], s[80:81]
	s_or_saveexec_b64 s[8:9], s[6:7]
	v_lshl_add_u32 v216, v128, 3, s33
	v_add_u32_e32 v184, s10, v216
	s_xor_b64 exec, exec, s[8:9]
	s_cbranch_execz .LBB0_745
	s_ashr_i32 s75, s74, 31
	s_lshl_b64 s[6:7], s[74:75], 2
	v_readlane_b32 s10, v255, 7
	s_add_u32 s6, s10, s6
	v_readlane_b32 s10, v255, 8
	s_addc_u32 s7, s10, s7
	v_ashrrev_i32_e32 v187, 31, v186
	v_lshl_add_u64 v[130:131], v[186:187], 2, s[6:7]
	s_nop 1
	v_mov_b32_e32 v126, v248
	v_readlane_b32 s6, v255, 2
	s_and_b64 s[10:11], s[38:39], s[80:81]
	s_waitcnt vmcnt(0)
	v_fmamk_f32 v126, v126, 0x39800000, v210
	v_cmp_gt_f32_e32 vcc, s27, v126
	v_mul_f32_e32 v127, 0x4f800000, v126
	v_add_lshl_u32 v133, s6, v186, 9
	v_cndmask_b32_e32 v126, v126, v127, vcc
	v_sqrt_f32_e32 v127, v126
	s_nop 0
	v_add_u32_e32 v128, -1, v127
	v_fma_f32 v129, -v128, v127, v126
	v_cmp_ge_f32_e64 s[6:7], 0, v129
	v_add_u32_e32 v129, 1, v127
	s_nop 0
	v_cndmask_b32_e64 v128, v127, v128, s[6:7]
	v_fma_f32 v127, -v129, v127, v126
	v_cmp_lt_f32_e64 s[6:7], 0, v127
	s_nop 1
	v_cndmask_b32_e64 v127, v128, v129, s[6:7]
	v_mul_f32_e32 v128, 0x37800000, v127
	v_cndmask_b32_e32 v127, v127, v128, vcc
	v_cmp_class_f32_e32 vcc, v126, v211
	s_nop 1
	v_cndmask_b32_e32 v126, v127, v126, vcc
	v_div_scale_f32 v127, s[6:7], v126, v126, 1.0
	v_rcp_f32_e32 v128, v127
	s_nop 0
	v_fma_f32 v129, -v127, v128, 1.0
	v_fmac_f32_e32 v128, v129, v128
	v_div_scale_f32 v129, vcc, 1.0, v126, 1.0
	v_mul_f32_e32 v132, v129, v128
	v_fma_f32 v134, -v127, v132, v129
	v_fmac_f32_e32 v132, v134, v128
	v_fma_f32 v127, -v127, v132, v129
	v_div_fmas_f32 v127, v127, v128, v132
	v_div_fixup_f32 v132, v127, v126, 1.0
	v_lshlrev_b32_e32 v134, 2, v216
	v_pk_mul_f32 v[128:129], v[112:113], v[132:133] op_sel_hi:[1,0]
	v_pk_mul_f32 v[126:127], v[110:111], v[132:133] op_sel_hi:[1,0]
	v_add3_u32 v136, s61, v133, v134
	ds_write_b128 v136, v[126:129]
	v_pk_mul_f32 v[128:129], v[48:49], v[132:133] op_sel_hi:[1,0]
	v_pk_mul_f32 v[126:127], v[46:47], v[132:133] op_sel_hi:[1,0]
	ds_write_b128 v136, v[126:129] offset:16
	s_nop 1
	v_mov_b32_e32 v126, v249
	s_waitcnt vmcnt(0)
	v_fmamk_f32 v126, v126, 0x39800000, v210
	v_cmp_gt_f32_e32 vcc, s27, v126
	v_mul_f32_e32 v127, 0x4f800000, v126
	s_nop 0
	v_cndmask_b32_e32 v126, v126, v127, vcc
	v_sqrt_f32_e32 v127, v126
	s_nop 0
	v_add_u32_e32 v128, -1, v127
	v_fma_f32 v129, -v128, v127, v126
	v_cmp_ge_f32_e64 s[6:7], 0, v129
	v_add_u32_e32 v129, 1, v127
	s_nop 0
	v_cndmask_b32_e64 v128, v127, v128, s[6:7]
	v_fma_f32 v127, -v129, v127, v126
	v_cmp_lt_f32_e64 s[6:7], 0, v127
	s_nop 1
	v_cndmask_b32_e64 v127, v128, v129, s[6:7]
	v_mul_f32_e32 v128, 0x37800000, v127
	v_cndmask_b32_e32 v127, v127, v128, vcc
	v_cmp_class_f32_e32 vcc, v126, v211
	s_nop 1
	v_cndmask_b32_e32 v126, v127, v126, vcc
	v_div_scale_f32 v127, s[6:7], v126, v126, 1.0
	v_rcp_f32_e32 v128, v127
	v_readlane_b32 s6, v255, 18
	v_fma_f32 v129, -v127, v128, 1.0
	v_fmac_f32_e32 v128, v129, v128
	v_div_scale_f32 v129, vcc, 1.0, v126, 1.0
	v_mul_f32_e32 v132, v129, v128
	v_fma_f32 v135, -v127, v132, v129
	v_fmac_f32_e32 v132, v135, v128
	v_fma_f32 v127, -v127, v132, v129
	v_div_fmas_f32 v127, v127, v128, v132
	v_div_fixup_f32 v132, v127, v126, 1.0
	v_pk_mul_f32 v[128:129], v[80:81], v[132:133] op_sel_hi:[1,0]
	v_pk_mul_f32 v[126:127], v[78:79], v[132:133] op_sel_hi:[1,0]
	v_add3_u32 v133, s6, v133, v134
	ds_write_b128 v133, v[126:129]
	v_pk_mul_f32 v[134:135], v[16:17], v[132:133] op_sel_hi:[1,0]
	v_pk_mul_f32 v[132:133], v[14:15], v[132:133] op_sel_hi:[1,0]
	s_mov_b64 s[6:7], 0
	s_andn2_b64 vcc, exec, s[10:11]
	ds_write_b128 v136, v[132:135] offset:2064
	s_cbranch_vccnz .LBB0_744
	v_add_u32_e32 v178, -14, v186
	s_ashr_i32 s77, s76, 31
	v_lshl_add_u64 v[132:133], s[76:77], 1, v[178:179]
	v_mov_b64_e32 v[134:135], s[42:43]
	v_mad_u64_u32 v[134:135], s[6:7], v132, s26, v[134:135]
	v_ashrrev_i32_e32 v185, 31, v184
	v_mad_i32_i24 v135, v133, s26, v135
	s_and_b32 s6, s76, 7
	v_lshl_add_u64 v[132:133], v[184:185], 2, v[134:135]
	s_cmp_lg_u32 s6, 7
	s_mov_b64 s[6:7], -1
	global_store_dwordx4 v[132:133], v[126:129], off
	s_cbranch_scc0 .LBB0_741
	s_nop 1
	v_mov_b32_e32 v134, v249
	s_waitcnt vmcnt(0)
	v_fmamk_f32 v134, v134, 0x39800000, v210
	v_mul_f32_e32 v135, 0x4f800000, v134
	v_cmp_gt_f32_e32 vcc, s27, v134
	s_nop 1
	v_cndmask_b32_e32 v134, v134, v135, vcc
	v_sqrt_f32_e32 v135, v134
	s_nop 0
	v_add_u32_e32 v136, -1, v135
	v_add_u32_e32 v137, 1, v135
	v_fma_f32 v138, -v136, v135, v134
	v_fma_f32 v139, -v137, v135, v134
	v_cmp_ge_f32_e64 s[6:7], 0, v138
	s_nop 1
	v_cndmask_b32_e64 v135, v135, v136, s[6:7]
	v_cmp_lt_f32_e64 s[6:7], 0, v139
	s_nop 1
	v_cndmask_b32_e64 v135, v135, v137, s[6:7]
	v_mul_f32_e32 v136, 0x37800000, v135
	v_cndmask_b32_e32 v135, v135, v136, vcc
	v_cmp_class_f32_e32 vcc, v134, v211
	s_nop 1
	v_cndmask_b32_e32 v134, v135, v134, vcc
	v_div_scale_f32 v135, s[6:7], v134, v134, 1.0
	v_rcp_f32_e32 v136, v135
	v_div_scale_f32 v137, vcc, 1.0, v134, 1.0
	s_mov_b64 s[6:7], 0
	v_fma_f32 v138, -v135, v136, 1.0
	v_fmac_f32_e32 v136, v138, v136
	v_mul_f32_e32 v138, v137, v136
	v_fma_f32 v139, -v135, v138, v137
	v_fmac_f32_e32 v138, v139, v136
	v_fma_f32 v135, -v135, v138, v137
	v_div_fmas_f32 v135, v135, v136, v138
	v_div_fixup_f32 v134, v135, v134, 1.0
	v_pk_mul_f32 v[136:137], v[16:17], v[134:135] op_sel_hi:[1,0]
	v_pk_mul_f32 v[134:135], v[14:15], v[134:135] op_sel_hi:[1,0]
	global_store_dwordx4 v[132:133], v[134:137], off offset:16
; #define RSTD(ai_, m_) (1.0f / sqrtf(sq[(ai_) * HALF + (m_) * 16] * (1.0f / DM) + EPS))
;     __device__ __forceinline__ void operator()(const f32x4 (&acc)[2][2][4][2], const Unit& u, int wr, int wc, int fr, int fq) const {
;     ...
;                 for (int n = 0; n < 2; ++n) { const f32x4 gh = acc[1][0][3][n] * RSTD(1, 3); *(f32x4*)(fix + ((size_t)u.pm * 2 + (fr - 14)) * DFF + j0 + 4 * n) = gh;
;                     if ((u.pm & 7) == 7) *(f32x4*)(out + O_PFFN + ((size_t)(u.pm >> 3) * 2 + (fr - 14)) * DFF + j0 + 4 * n) = gh; }
.LBB0_741:
	s_andn2_b64 vcc, exec, s[6:7]
	s_cbranch_vccnz .LBB0_743
	s_ashr_i32 s6, s76, 3
	s_ashr_i32 s7, s6, 31
	v_lshl_add_u64 v[134:135], s[6:7], 1, v[178:179]
	v_readlane_b32 s6, v255, 16
	v_readlane_b32 s7, v255, 17
	v_lshlrev_b64 v[138:139], 2, v[184:185]
	s_nop 0
	v_mov_b64_e32 v[136:137], s[6:7]
	v_mad_u64_u32 v[136:137], s[6:7], v134, s26, v[136:137]
	v_mad_i32_i24 v137, v135, s26, v137
	v_lshl_add_u64 v[136:137], v[136:137], 0, v[138:139]
	global_store_dwordx4 v[136:137], v[126:129], off
	s_nop 1
	s_nop 0
	v_mov_b64_e32 v[126:127], s[34:35]
	v_mad_u64_u32 v[126:127], s[6:7], v134, s26, v[126:127]
	v_mad_i32_i24 v127, v135, s26, v127
	v_lshl_add_u64 v[126:127], v[126:127], 0, v[138:139]
	v_mov_b32_e32 v128, v249
	s_waitcnt vmcnt(0)
	v_fmamk_f32 v128, v128, 0x39800000, v210
	v_mul_f32_e32 v129, 0x4f800000, v128
	v_cmp_gt_f32_e32 vcc, s27, v128
	s_nop 1
	v_cndmask_b32_e32 v128, v128, v129, vcc
	v_sqrt_f32_e32 v129, v128
	s_nop 0
	v_add_u32_e32 v130, -1, v129
	v_add_u32_e32 v131, 1, v129
	v_fma_f32 v134, -v130, v129, v128
	v_fma_f32 v135, -v131, v129, v128
	v_cmp_ge_f32_e64 s[6:7], 0, v134
	s_nop 1
	v_cndmask_b32_e64 v129, v129, v130, s[6:7]
	v_cmp_lt_f32_e64 s[6:7], 0, v135
	s_nop 1
	v_cndmask_b32_e64 v129, v129, v131, s[6:7]
	v_mul_f32_e32 v130, 0x37800000, v129
	v_cndmask_b32_e32 v129, v129, v130, vcc
	v_cmp_class_f32_e32 vcc, v128, v211
	s_nop 1
	v_cndmask_b32_e32 v128, v129, v128, vcc
	v_div_scale_f32 v129, s[6:7], v128, v128, 1.0
	v_rcp_f32_e32 v130, v129
	v_div_scale_f32 v131, vcc, 1.0, v128, 1.0
	v_fma_f32 v134, -v129, v130, 1.0
	v_fmac_f32_e32 v130, v134, v130
	v_mul_f32_e32 v134, v131, v130
	v_fma_f32 v135, -v129, v134, v131
	v_fmac_f32_e32 v134, v135, v130
	v_fma_f32 v129, -v129, v134, v131
	v_div_fmas_f32 v129, v129, v130, v134
	v_add_co_u32_e32 v130, vcc, 0x9630000, v126
	v_div_fixup_f32 v126, v129, v128, 1.0
	s_nop 0
	v_addc_co_u32_e32 v131, vcc, 0, v127, vcc
	v_pk_mul_f32 v[128:129], v[16:17], v[126:127] op_sel_hi:[1,0]
	v_pk_mul_f32 v[126:127], v[14:15], v[126:127] op_sel_hi:[1,0]
	global_store_dwordx4 v[132:133], v[126:129], off offset:16
	global_store_dwordx4 v[130:131], v[126:129], off offset:16
